# job3: next-tile global loads issued inside the QK MFMA chain (one per two MFMAs, scalar running base) instead of in the LDS store phase
# speedup vs baseline: 1.0266x; 1.0018x over previous
.LBB0_939:
	s_add_i32 s12, s11, 0xffffff80
	v_add_u32_e32 v205, v226, v204
	v_cmp_lt_i32_e32 vcc, s12, v227
	s_waitcnt lgkmcnt(0)
	s_barrier
	s_waitcnt vmcnt(7)
	ds_write_b128 v205, v[166:169]
	s_waitcnt vmcnt(6)
	ds_write_b128 v205, v[170:173] offset:9472
	s_waitcnt vmcnt(5)
	ds_write_b128 v205, v[174:177] offset:18944
	s_waitcnt vmcnt(4)
	ds_write_b128 v205, v[178:181] offset:28416
	s_waitcnt vmcnt(3)
	ds_write_b128 v205, v[182:185] offset:37888
	s_waitcnt vmcnt(2)
	ds_write_b128 v205, v[186:189] offset:47360
	s_waitcnt vmcnt(1)
	ds_write_b128 v205, v[190:193] offset:56832
	s_waitcnt vmcnt(0)
	ds_write_b128 v228, v[194:197]
	s_and_saveexec_b64 s[6:7], vcc
	v_add_u32_e32 v148, v225, v210
	ds_write_b128 v148, v[162:165] offset:512
	s_or_b64 exec, exec, s[6:7]
	s_add_u32 s60, s34, 0x16d10000
	s_addc_u32 s61, s35, 0
	s_waitcnt lgkmcnt(0)
	s_barrier
	s_cmp_ge_i32 s12, s10
	s_cbranch_scc1 .LBB0_947
	v_add_u32_e32 v229, v224, v198
	ds_read_b128 v[130:133], v229
	ds_read_b128 v[134:137], v223
	ds_read_b128 v[146:149], v229 offset:32
	ds_read_b128 v[150:153], v223 offset:1024
	ds_read_b128 v[232:235], v229 offset:64
	ds_read_b128 v[236:239], v223 offset:2048
	ds_read_b128 v[240:243], v229 offset:96
	ds_read_b128 v[246:249], v223 offset:3072
	s_waitcnt lgkmcnt(6)
	v_mfma_f32_32x32x16_bf16 v[130:145], v[130:133], v[134:137], 0
	v_lshl_add_u64 v[250:251], s[60:61], 0, v[214:215]
	global_load_dwordx4 v[166:169], v[250:251], off
	s_add_u32 s60, s60, s24
	s_addc_u32 s61, s61, s25
	s_waitcnt lgkmcnt(4)
	v_mfma_f32_32x32x16_bf16 v[146:161], v[146:149], v[150:153], 0
	s_waitcnt lgkmcnt(2)
	v_mfma_f32_32x32x16_bf16 v[130:145], v[232:235], v[236:239], v[130:145]
	ds_read_b128 v[232:235], v229 offset:128
	ds_read_b128 v[236:239], v223 offset:4096
	v_lshl_add_u64 v[252:253], s[60:61], 0, v[214:215]
	global_load_dwordx4 v[170:173], v[252:253], off
	s_add_u32 s60, s60, s24
	s_addc_u32 s61, s61, s25
	s_waitcnt lgkmcnt(2)
	v_mfma_f32_32x32x16_bf16 v[146:161], v[240:243], v[246:249], v[146:161]
	ds_read_b128 v[240:243], v229 offset:160
	ds_read_b128 v[246:249], v223 offset:5120
	s_waitcnt lgkmcnt(2)
	v_mfma_f32_32x32x16_bf16 v[130:145], v[232:235], v[236:239], v[130:145]
	ds_read_b128 v[232:235], v229 offset:192
	ds_read_b128 v[236:239], v223 offset:6144
	v_lshl_add_u64 v[250:251], s[60:61], 0, v[214:215]
	global_load_dwordx4 v[174:177], v[250:251], off
	s_add_u32 s60, s60, s24
	s_addc_u32 s61, s61, s25
	s_waitcnt lgkmcnt(2)
	v_mfma_f32_32x32x16_bf16 v[146:161], v[240:243], v[246:249], v[146:161]
	ds_read_b128 v[240:243], v229 offset:224
	ds_read_b128 v[246:249], v223 offset:7168
	s_waitcnt lgkmcnt(2)
	v_mfma_f32_32x32x16_bf16 v[130:145], v[232:235], v[236:239], v[130:145]
	ds_read_b128 v[232:235], v229 offset:256
	ds_read_b128 v[236:239], v223 offset:8192
	v_lshl_add_u64 v[252:253], s[60:61], 0, v[214:215]
	global_load_dwordx4 v[178:181], v[252:253], off
	s_add_u32 s60, s60, s24
	s_addc_u32 s61, s61, s25
	s_waitcnt lgkmcnt(2)
	v_mfma_f32_32x32x16_bf16 v[146:161], v[240:243], v[246:249], v[146:161]
	ds_read_b128 v[240:243], v229 offset:288
	ds_read_b128 v[246:249], v223 offset:9216
	s_waitcnt lgkmcnt(2)
	v_mfma_f32_32x32x16_bf16 v[130:145], v[232:235], v[236:239], v[130:145]
	ds_read_b128 v[232:235], v229 offset:320
	ds_read_b128 v[236:239], v223 offset:10240
	v_lshl_add_u64 v[250:251], s[60:61], 0, v[214:215]
	global_load_dwordx4 v[182:185], v[250:251], off
	s_add_u32 s60, s60, s24
	s_addc_u32 s61, s61, s25
	s_waitcnt lgkmcnt(2)
	v_mfma_f32_32x32x16_bf16 v[146:161], v[240:243], v[246:249], v[146:161]
	ds_read_b128 v[240:243], v229 offset:352
	ds_read_b128 v[246:249], v223 offset:11264
	s_waitcnt lgkmcnt(2)
	v_mfma_f32_32x32x16_bf16 v[130:145], v[232:235], v[236:239], v[130:145]
	ds_read_b128 v[232:235], v229 offset:384
	ds_read_b128 v[236:239], v223 offset:12288
	v_lshl_add_u64 v[252:253], s[60:61], 0, v[214:215]
	global_load_dwordx4 v[186:189], v[252:253], off
	s_add_u32 s60, s60, s24
	s_addc_u32 s61, s61, s25
	s_waitcnt lgkmcnt(2)
	v_mfma_f32_32x32x16_bf16 v[146:161], v[240:243], v[246:249], v[146:161]
	ds_read_b128 v[240:243], v229 offset:416
	ds_read_b128 v[246:249], v223 offset:13312
	s_waitcnt lgkmcnt(2)
	v_mfma_f32_32x32x16_bf16 v[130:145], v[232:235], v[236:239], v[130:145]
	ds_read_b128 v[232:235], v229 offset:448
	ds_read_b128 v[236:239], v223 offset:14336
	v_lshl_add_u64 v[250:251], s[60:61], 0, v[214:215]
	global_load_dwordx4 v[190:193], v[250:251], off
	s_add_u32 s60, s60, s24
	s_addc_u32 s61, s61, s25
	s_waitcnt lgkmcnt(2)
	v_mfma_f32_32x32x16_bf16 v[146:161], v[240:243], v[246:249], v[146:161]
	ds_read_b128 v[240:243], v229 offset:480
	ds_read_b128 v[246:249], v223 offset:15360
	s_waitcnt lgkmcnt(2)
	v_mfma_f32_32x32x16_bf16 v[130:145], v[232:235], v[236:239], v[130:145]
	ds_read_b128 v[232:235], v229 offset:512
	ds_read_b128 v[236:239], v223 offset:16384
	v_lshl_add_u64 v[252:253], s[60:61], 0, v[214:215]
	global_load_dwordx4 v[194:197], v[252:253], off
	s_waitcnt lgkmcnt(2)
	v_mfma_f32_32x32x16_bf16 v[146:161], v[240:243], v[246:249], v[146:161]
	ds_read_b128 v[240:243], v229 offset:544
	ds_read_b128 v[246:249], v223 offset:17408
	s_waitcnt lgkmcnt(2)
	v_mfma_f32_32x32x16_bf16 v[130:145], v[232:235], v[236:239], v[130:145]
	v_cmp_lt_i32_e32 vcc, s11, v227
	v_lshl_add_u64 v[250:251], s[34:35], 0, v[212:213]
	s_and_saveexec_b64 s[6:7], vcc
	s_cbranch_execz .Lj3ld_norka
	global_load_dwordx4 v[162:165], v[250:251], off
.Lj3ld_norka:
	s_or_b64 exec, exec, s[6:7]
	s_waitcnt lgkmcnt(0)
	v_mfma_f32_32x32x16_bf16 v[146:161], v[240:243], v[246:249], v[146:161]
	s_nop 11
	v_pk_add_f32 v[146:147], v[130:131], v[146:147]
	v_pk_add_f32 v[132:133], v[132:133], v[148:149]
	v_max_f32_e32 v130, v146, v147
	v_pk_add_f32 v[134:135], v[134:135], v[150:151]
	v_max3_f32 v130, v130, v132, v133
	v_pk_add_f32 v[136:137], v[136:137], v[152:153]
	v_max3_f32 v130, v130, v134, v135
	v_mbcnt_hi_u32_b32 v131, -1, v217
	v_pk_add_f32 v[138:139], v[138:139], v[154:155]
	v_max3_f32 v130, v130, v136, v137
	v_and_b32_e32 v149, 64, v131
	v_pk_add_f32 v[140:141], v[140:141], v[156:157]
	v_max3_f32 v130, v130, v138, v139
	v_xor_b32_e32 v148, 32, v131
	v_add_u32_e32 v149, 64, v149
	v_pk_add_f32 v[142:143], v[142:143], v[158:159]
	v_max3_f32 v130, v130, v140, v141
	v_cmp_lt_i32_e32 vcc, v148, v149
	v_pk_add_f32 v[144:145], v[144:145], v[160:161]
	v_max3_f32 v130, v130, v142, v143
	v_cndmask_b32_e32 v131, v131, v148, vcc
	v_max3_f32 v130, v130, v144, v145
	v_lshlrev_b32_e32 v131, 2, v131
	ds_bpermute_b32 v131, v131, v130
	s_waitcnt lgkmcnt(0)
	ds_read_b64_tr_b16 v[232:233], v222
	ds_read_b64_tr_b16 v[234:235], v222 offset:4736
	ds_read_b64_tr_b16 v[236:237], v222 offset:64
	ds_read_b64_tr_b16 v[238:239], v222 offset:4800
	ds_read_b64_tr_b16 v[240:241], v222 offset:128
	ds_read_b64_tr_b16 v[242:243], v222 offset:4864
	ds_read_b64_tr_b16 v[246:247], v222 offset:192
	ds_read_b64_tr_b16 v[248:249], v222 offset:4928
	v_max3_f32 v229, v230, v130, v131
	v_sub_f32_e32 v130, v230, v229
	v_exp_f32_e32 v130, v130
	s_nop 0
	v_cmp_neq_f32_e32 vcc, 1.0, v130
	s_cbranch_vccz .LBB0_946
	v_pk_mul_f32 v[128:129], v[128:129], v[130:131] op_sel_hi:[1,0]
	v_pk_mul_f32 v[126:127], v[126:127], v[130:131] op_sel_hi:[1,0]
	v_pk_mul_f32 v[124:125], v[124:125], v[130:131] op_sel_hi:[1,0]
	v_pk_mul_f32 v[122:123], v[122:123], v[130:131] op_sel_hi:[1,0]
	v_pk_mul_f32 v[120:121], v[120:121], v[130:131] op_sel_hi:[1,0]
	v_pk_mul_f32 v[118:119], v[118:119], v[130:131] op_sel_hi:[1,0]
	v_pk_mul_f32 v[116:117], v[116:117], v[130:131] op_sel_hi:[1,0]
	v_pk_mul_f32 v[114:115], v[114:115], v[130:131] op_sel_hi:[1,0]
	v_pk_mul_f32 v[112:113], v[112:113], v[130:131] op_sel_hi:[1,0]
	v_pk_mul_f32 v[110:111], v[110:111], v[130:131] op_sel_hi:[1,0]
	v_pk_mul_f32 v[108:109], v[108:109], v[130:131] op_sel_hi:[1,0]
	v_pk_mul_f32 v[106:107], v[106:107], v[130:131] op_sel_hi:[1,0]
	v_pk_mul_f32 v[104:105], v[104:105], v[130:131] op_sel_hi:[1,0]
	v_pk_mul_f32 v[102:103], v[102:103], v[130:131] op_sel_hi:[1,0]
	v_pk_mul_f32 v[100:101], v[100:101], v[130:131] op_sel_hi:[1,0]
	v_pk_mul_f32 v[98:99], v[98:99], v[130:131] op_sel_hi:[1,0]
	v_pk_mul_f32 v[96:97], v[96:97], v[130:131] op_sel_hi:[1,0]
	v_pk_mul_f32 v[94:95], v[94:95], v[130:131] op_sel_hi:[1,0]
	v_pk_mul_f32 v[92:93], v[92:93], v[130:131] op_sel_hi:[1,0]
	v_pk_mul_f32 v[90:91], v[90:91], v[130:131] op_sel_hi:[1,0]
	v_pk_mul_f32 v[88:89], v[88:89], v[130:131] op_sel_hi:[1,0]
	v_pk_mul_f32 v[86:87], v[86:87], v[130:131] op_sel_hi:[1,0]
	v_pk_mul_f32 v[84:85], v[84:85], v[130:131] op_sel_hi:[1,0]
	v_pk_mul_f32 v[82:83], v[82:83], v[130:131] op_sel_hi:[1,0]
	v_pk_mul_f32 v[80:81], v[80:81], v[130:131] op_sel_hi:[1,0]
	v_pk_mul_f32 v[78:79], v[78:79], v[130:131] op_sel_hi:[1,0]
	v_pk_mul_f32 v[76:77], v[76:77], v[130:131] op_sel_hi:[1,0]
	v_pk_mul_f32 v[74:75], v[74:75], v[130:131] op_sel_hi:[1,0]
	v_pk_mul_f32 v[72:73], v[72:73], v[130:131] op_sel_hi:[1,0]
	v_pk_mul_f32 v[70:71], v[70:71], v[130:131] op_sel_hi:[1,0]
	v_pk_mul_f32 v[68:69], v[68:69], v[130:131] op_sel_hi:[1,0]
	v_pk_mul_f32 v[66:67], v[66:67], v[130:131] op_sel_hi:[1,0]
	v_pk_mul_f32 v[64:65], v[64:65], v[130:131] op_sel_hi:[1,0]
	v_pk_mul_f32 v[62:63], v[62:63], v[130:131] op_sel_hi:[1,0]
	v_pk_mul_f32 v[60:61], v[60:61], v[130:131] op_sel_hi:[1,0]
	v_pk_mul_f32 v[58:59], v[58:59], v[130:131] op_sel_hi:[1,0]
	v_pk_mul_f32 v[56:57], v[56:57], v[130:131] op_sel_hi:[1,0]
	v_pk_mul_f32 v[54:55], v[54:55], v[130:131] op_sel_hi:[1,0]
	v_pk_mul_f32 v[52:53], v[52:53], v[130:131] op_sel_hi:[1,0]
	v_pk_mul_f32 v[50:51], v[50:51], v[130:131] op_sel_hi:[1,0]
	v_pk_mul_f32 v[48:49], v[48:49], v[130:131] op_sel_hi:[1,0]
	v_pk_mul_f32 v[46:47], v[46:47], v[130:131] op_sel_hi:[1,0]
	v_pk_mul_f32 v[44:45], v[44:45], v[130:131] op_sel_hi:[1,0]
	v_pk_mul_f32 v[42:43], v[42:43], v[130:131] op_sel_hi:[1,0]
	v_pk_mul_f32 v[40:41], v[40:41], v[130:131] op_sel_hi:[1,0]
	v_pk_mul_f32 v[38:39], v[38:39], v[130:131] op_sel_hi:[1,0]
	v_pk_mul_f32 v[36:37], v[36:37], v[130:131] op_sel_hi:[1,0]
	v_pk_mul_f32 v[34:35], v[34:35], v[130:131] op_sel_hi:[1,0]
	v_pk_mul_f32 v[32:33], v[32:33], v[130:131] op_sel_hi:[1,0]
	v_pk_mul_f32 v[30:31], v[30:31], v[130:131] op_sel_hi:[1,0]
	v_pk_mul_f32 v[28:29], v[28:29], v[130:131] op_sel_hi:[1,0]
	v_pk_mul_f32 v[26:27], v[26:27], v[130:131] op_sel_hi:[1,0]
	v_pk_mul_f32 v[24:25], v[24:25], v[130:131] op_sel_hi:[1,0]
	v_pk_mul_f32 v[22:23], v[22:23], v[130:131] op_sel_hi:[1,0]
	v_pk_mul_f32 v[20:21], v[20:21], v[130:131] op_sel_hi:[1,0]
	v_pk_mul_f32 v[18:19], v[18:19], v[130:131] op_sel_hi:[1,0]
	v_pk_mul_f32 v[16:17], v[16:17], v[130:131] op_sel_hi:[1,0]
	v_pk_mul_f32 v[14:15], v[14:15], v[130:131] op_sel_hi:[1,0]
	v_pk_mul_f32 v[12:13], v[12:13], v[130:131] op_sel_hi:[1,0]
	v_pk_mul_f32 v[10:11], v[10:11], v[130:131] op_sel_hi:[1,0]
	v_pk_mul_f32 v[8:9], v[8:9], v[130:131] op_sel_hi:[1,0]
	v_pk_mul_f32 v[6:7], v[6:7], v[130:131] op_sel_hi:[1,0]
	v_pk_mul_f32 v[4:5], v[4:5], v[130:131] op_sel_hi:[1,0]
	v_pk_mul_f32 v[2:3], v[2:3], v[130:131] op_sel_hi:[1,0]

.LBB0_947:
	v_mov_b32_e32 v229, v230
	v_lshl_add_u64 v[250:251], s[60:61], 0, v[214:215]
	global_load_dwordx4 v[166:169], v[250:251], off
	s_add_u32 s60, s60, s24
	s_addc_u32 s61, s61, s25
	v_lshl_add_u64 v[252:253], s[60:61], 0, v[214:215]
	global_load_dwordx4 v[170:173], v[252:253], off
	s_add_u32 s60, s60, s24
	s_addc_u32 s61, s61, s25
	v_lshl_add_u64 v[250:251], s[60:61], 0, v[214:215]
	global_load_dwordx4 v[174:177], v[250:251], off
	s_add_u32 s60, s60, s24
	s_addc_u32 s61, s61, s25
	v_lshl_add_u64 v[252:253], s[60:61], 0, v[214:215]
	global_load_dwordx4 v[178:181], v[252:253], off
	s_add_u32 s60, s60, s24
	s_addc_u32 s61, s61, s25
	v_lshl_add_u64 v[250:251], s[60:61], 0, v[214:215]
	global_load_dwordx4 v[182:185], v[250:251], off
	s_add_u32 s60, s60, s24
	s_addc_u32 s61, s61, s25
	v_lshl_add_u64 v[252:253], s[60:61], 0, v[214:215]
	global_load_dwordx4 v[186:189], v[252:253], off
	s_add_u32 s60, s60, s24
	s_addc_u32 s61, s61, s25
	v_lshl_add_u64 v[250:251], s[60:61], 0, v[214:215]
	global_load_dwordx4 v[190:193], v[250:251], off
	s_add_u32 s60, s60, s24
	s_addc_u32 s61, s61, s25
	v_lshl_add_u64 v[252:253], s[60:61], 0, v[214:215]
	global_load_dwordx4 v[194:197], v[252:253], off
	v_cmp_lt_i32_e32 vcc, s11, v227
	v_lshl_add_u64 v[250:251], s[34:35], 0, v[212:213]
	s_and_saveexec_b64 s[6:7], vcc
	s_cbranch_execz .Lj3ld_norkb
	global_load_dwordx4 v[162:165], v[250:251], off
.Lj3ld_norkb:
	s_or_b64 exec, exec, s[6:7]
.LBB0_948:
	s_addk_i32 s11, 0x80
	v_lshl_add_u64 v[212:213], v[212:213], 0, s[24:25]
	s_cmpk_eq_i32 s11, 0x1000
	v_lshl_add_u64 v[214:215], v[214:215], 0, s[26:27]
	s_cbranch_scc1 .LBB0_950
	v_mov_b32_e32 v230, v229
	s_branch .LBB0_939
